# v4 + flat release: all workgroups poll TOPGEN directly, per-XCD XGEN relay removed
# speedup vs baseline: 1.0126x; 1.0018x over previous
.LBB0_147:
	s_or_b64 exec, exec, s[14:15]
	v_cvt_f32_u32_e32 v4, v2
	s_waitcnt vmcnt(0)
	v_readfirstlane_b32 s3, v3
	v_sub_u32_e32 v3, 0, v2
	v_rcp_iflag_f32_e32 v4, v4
	v_add_u32_e32 v5, s3, v1
	v_mul_f32_e32 v4, 0x4f7ffffe, v4
	v_cvt_u32_f32_e32 v4, v4
	v_mul_lo_u32 v1, v3, v4
	v_mul_hi_u32 v1, v4, v1
	v_add_u32_e32 v1, v4, v1
	v_mul_hi_u32 v1, v5, v1
	v_mul_lo_u32 v3, v1, v2
	v_sub_u32_e32 v3, v5, v3
	v_add_u32_e32 v4, 1, v1
	v_cmp_ge_u32_e32 vcc, v3, v2
	s_nop 1
	v_cndmask_b32_e32 v1, v1, v4, vcc
	v_sub_u32_e32 v4, v3, v2
	v_cndmask_b32_e32 v3, v3, v4, vcc
	v_add_u32_e32 v4, 1, v1
	v_cmp_ge_u32_e32 vcc, v3, v2
	v_add_u32_e32 v3, 1, v5
	s_nop 0
	v_cndmask_b32_e32 v1, v1, v4, vcc
	v_mul_lo_u32 v4, v2, v1
	v_add_u32_e32 v2, v4, v2
	v_cmp_ne_u32_e32 vcc, v3, v2
	s_and_saveexec_b64 s[12:13], vcc
	s_xor_b64 s[12:13], exec, s[12:13]
	s_cbranch_execz .LBB0_161
	s_waitcnt lgkmcnt(0)
	v_mov_b32_e32 v0, 0x3600
	global_load_dword v0, v0, s[42:43] sc1
	s_add_u32 s16, s42, 0x3600
	s_addc_u32 s17, s43, 0
	s_waitcnt vmcnt(0)
	v_cmp_eq_u32_e32 vcc, v0, v1
	s_and_saveexec_b64 s[14:15], vcc
	s_cbranch_execz .LBB0_160
	s_mov_b32 s3, 1
	s_mov_b64 s[18:19], 0
	v_mov_b32_e32 v0, 0
	s_branch .LBB0_151

.LBB0_178:
	s_or_b64 exec, exec, s[12:13]
	s_mov_b64 s[12:13], exec
	v_mbcnt_lo_u32_b32 v0, s12, 0
	v_mbcnt_hi_u32_b32 v0, s13, v0
	v_cmp_eq_u32_e32 vcc, 0, v0
	s_waitcnt vmcnt(0)
	s_and_saveexec_b64 s[14:15], vcc
	s_cbranch_execz .LBB0_180
	s_bcnt1_i32_b64 s3, s[12:13]
	v_mov_b32_e32 v0, 0x2000
	v_mov_b32_e32 v1, s3
.LBB0_180:
	s_or_b64 exec, exec, s[14:15]
	s_waitcnt vmcnt(0)
	s_branch .LBB0_181

.LBB0_405:
	s_or_b64 exec, exec, s[12:13]
	s_mov_b64 s[12:13], exec
	v_mbcnt_lo_u32_b32 v0, s12, 0
	v_mbcnt_hi_u32_b32 v0, s13, v0
	v_cmp_eq_u32_e32 vcc, 0, v0
	s_waitcnt vmcnt(0)
	s_and_saveexec_b64 s[14:15], vcc
	s_cbranch_execz .LBB0_407
	s_bcnt1_i32_b64 s3, s[12:13]
	v_mov_b32_e32 v0, 0x2000
	v_mov_b32_e32 v1, s3
.LBB0_407:
	s_or_b64 exec, exec, s[14:15]
	s_waitcnt vmcnt(0)
	s_branch .LBB0_408

.LBB0_531:
	s_or_b64 exec, exec, s[12:13]
	s_mov_b64 s[12:13], exec
	v_mbcnt_lo_u32_b32 v0, s12, 0
	v_mbcnt_hi_u32_b32 v0, s13, v0
	v_cmp_eq_u32_e32 vcc, 0, v0
	s_waitcnt vmcnt(0)
	s_and_saveexec_b64 s[14:15], vcc
	s_cbranch_execz .LBB0_533
	s_bcnt1_i32_b64 s3, s[12:13]
	v_mov_b32_e32 v0, 0x2000
	v_mov_b32_e32 v1, s3
.LBB0_533:
	s_or_b64 exec, exec, s[14:15]
	s_waitcnt vmcnt(0)
	s_branch .LBB0_534

.LBB0_601:
	s_or_b64 exec, exec, s[12:13]
	s_mov_b64 s[12:13], exec
	v_mbcnt_lo_u32_b32 v0, s12, 0
	v_mbcnt_hi_u32_b32 v0, s13, v0
	v_cmp_eq_u32_e32 vcc, 0, v0
	s_waitcnt vmcnt(0)
	s_and_saveexec_b64 s[14:15], vcc
	s_cbranch_execz .LBB0_603
	s_bcnt1_i32_b64 s3, s[12:13]
	v_mov_b32_e32 v0, 0x2000
	v_mov_b32_e32 v1, s3
.LBB0_603:
	s_or_b64 exec, exec, s[14:15]
	s_waitcnt vmcnt(0)
	s_branch .LBB0_604

.LBB0_678:
	s_or_b64 exec, exec, s[12:13]
	s_mov_b64 s[12:13], exec
	v_mbcnt_lo_u32_b32 v0, s12, 0
	v_mbcnt_hi_u32_b32 v0, s13, v0
	v_cmp_eq_u32_e32 vcc, 0, v0
	s_waitcnt vmcnt(0)
	s_and_saveexec_b64 s[14:15], vcc
	s_cbranch_execz .LBB0_680
	s_bcnt1_i32_b64 s3, s[12:13]
	v_mov_b32_e32 v0, 0x2000
	v_mov_b32_e32 v1, s3
.LBB0_680:
	s_or_b64 exec, exec, s[14:15]
	s_waitcnt vmcnt(0)
	s_branch .LBB0_681

.LBB0_749:
	s_or_b64 exec, exec, s[12:13]
	s_mov_b64 s[12:13], exec
	v_mbcnt_lo_u32_b32 v0, s12, 0
	v_mbcnt_hi_u32_b32 v0, s13, v0
	v_cmp_eq_u32_e32 vcc, 0, v0
	s_waitcnt vmcnt(0)
	s_and_saveexec_b64 s[14:15], vcc
	s_cbranch_execz .LBB0_751
	s_bcnt1_i32_b64 s3, s[12:13]
	v_mov_b32_e32 v0, 0x2000
	v_mov_b32_e32 v1, s3
.LBB0_751:
	s_or_b64 exec, exec, s[14:15]
	s_waitcnt vmcnt(0)
	s_branch .LBB0_752

.LBB0_808:
	s_or_b64 exec, exec, s[12:13]
	s_mov_b64 s[12:13], exec
	v_mbcnt_lo_u32_b32 v0, s12, 0
	v_mbcnt_hi_u32_b32 v0, s13, v0
	v_cmp_eq_u32_e32 vcc, 0, v0
	s_waitcnt vmcnt(0)
	s_and_saveexec_b64 s[14:15], vcc
	s_cbranch_execz .LBB0_810
	s_bcnt1_i32_b64 s3, s[12:13]
	v_mov_b32_e32 v0, 0x2000
	v_mov_b32_e32 v1, s3
.LBB0_810:
	s_or_b64 exec, exec, s[14:15]
	s_waitcnt vmcnt(0)
	s_branch .LBB0_811

.LBB0_961:
	s_or_b64 exec, exec, s[12:13]
	s_mov_b64 s[12:13], exec
	v_mbcnt_lo_u32_b32 v0, s12, 0
	v_mbcnt_hi_u32_b32 v0, s13, v0
	v_cmp_eq_u32_e32 vcc, 0, v0
	s_waitcnt vmcnt(0)
	s_and_saveexec_b64 s[14:15], vcc
	s_cbranch_execz .LBB0_963
	s_bcnt1_i32_b64 s3, s[12:13]
	v_mov_b32_e32 v0, 0x2000
	v_mov_b32_e32 v1, s3
.LBB0_963:
	s_or_b64 exec, exec, s[14:15]
	s_waitcnt vmcnt(0)
	s_branch .LBB0_964

.LBB0_1026:
	s_or_b64 exec, exec, s[12:13]
	s_mov_b64 s[12:13], exec
	v_mbcnt_lo_u32_b32 v0, s12, 0
	v_mbcnt_hi_u32_b32 v0, s13, v0
	v_cmp_eq_u32_e32 vcc, 0, v0
	s_waitcnt vmcnt(0)
	s_and_saveexec_b64 s[14:15], vcc
	s_cbranch_execz .LBB0_1028
	s_bcnt1_i32_b64 s3, s[12:13]
	v_mov_b32_e32 v0, 0x2000
	v_mov_b32_e32 v1, s3
.LBB0_1028:
	s_or_b64 exec, exec, s[14:15]
	s_waitcnt vmcnt(0)
	s_branch .LBB0_1029

.LBB0_1214:
	s_or_b64 exec, exec, s[12:13]
	s_mov_b64 s[12:13], exec
	v_mbcnt_lo_u32_b32 v0, s12, 0
	v_mbcnt_hi_u32_b32 v0, s13, v0
	v_cmp_eq_u32_e32 vcc, 0, v0
	s_waitcnt vmcnt(0)
	s_and_saveexec_b64 s[14:15], vcc
	s_cbranch_execz .LBB0_1216
	s_bcnt1_i32_b64 s3, s[12:13]
	v_mov_b32_e32 v0, 0x2000
	v_mov_b32_e32 v1, s3
.LBB0_1216:
	s_or_b64 exec, exec, s[14:15]
	s_waitcnt vmcnt(0)
	s_branch .LBB0_1217

.LBB0_1413:
	s_or_b64 exec, exec, s[12:13]
	s_mov_b64 s[12:13], exec
	v_mbcnt_lo_u32_b32 v0, s12, 0
	v_mbcnt_hi_u32_b32 v0, s13, v0
	v_cmp_eq_u32_e32 vcc, 0, v0
	s_waitcnt vmcnt(0)
	s_and_saveexec_b64 s[14:15], vcc
	s_cbranch_execz .LBB0_1415
	s_bcnt1_i32_b64 s3, s[12:13]
	v_mov_b32_e32 v0, 0x2000
	v_mov_b32_e32 v1, s3
.LBB0_1415:
	s_or_b64 exec, exec, s[14:15]
	s_waitcnt vmcnt(0)
	s_branch .LBB0_1416

.LBB0_1453:
	s_or_b64 exec, exec, s[12:13]
	v_cvt_f32_u32_e32 v4, v2
	s_waitcnt vmcnt(0)
	v_readfirstlane_b32 s3, v3
	v_sub_u32_e32 v3, 0, v2
	v_rcp_iflag_f32_e32 v4, v4
	v_add_u32_e32 v5, s3, v1
	v_mul_f32_e32 v4, 0x4f7ffffe, v4
	v_cvt_u32_f32_e32 v4, v4
	v_mul_lo_u32 v1, v3, v4
	v_mul_hi_u32 v1, v4, v1
	v_add_u32_e32 v1, v4, v1
	v_mul_hi_u32 v1, v5, v1
	v_mul_lo_u32 v3, v1, v2
	v_sub_u32_e32 v3, v5, v3
	v_add_u32_e32 v4, 1, v1
	v_cmp_ge_u32_e32 vcc, v3, v2
	s_nop 1
	v_cndmask_b32_e32 v1, v1, v4, vcc
	v_sub_u32_e32 v4, v3, v2
	v_cndmask_b32_e32 v3, v3, v4, vcc
	v_add_u32_e32 v4, 1, v1
	v_cmp_ge_u32_e32 vcc, v3, v2
	v_add_u32_e32 v3, 1, v5
	s_nop 0
	v_cndmask_b32_e32 v1, v1, v4, vcc
	v_mul_lo_u32 v4, v2, v1
	v_add_u32_e32 v2, v4, v2
	v_cmp_ne_u32_e32 vcc, v3, v2
	s_and_saveexec_b64 s[10:11], vcc
	s_xor_b64 s[10:11], exec, s[10:11]
	s_cbranch_execz .LBB0_1467
	s_waitcnt lgkmcnt(0)
	v_mov_b32_e32 v0, 0x3600
	global_load_dword v0, v0, s[42:43] sc1
	s_add_u32 s14, s42, 0x3600
	s_addc_u32 s15, s43, 0
	s_waitcnt vmcnt(0)
	v_cmp_eq_u32_e32 vcc, v0, v1
	s_and_saveexec_b64 s[12:13], vcc
	s_cbranch_execz .LBB0_1466
	s_mov_b32 s3, 1
	s_mov_b64 s[16:17], 0
	v_mov_b32_e32 v0, 0
	s_branch .LBB0_1457

.LBB0_1484:
	s_or_b64 exec, exec, s[10:11]
	s_mov_b64 s[10:11], exec
	v_mbcnt_lo_u32_b32 v0, s10, 0
	v_mbcnt_hi_u32_b32 v0, s11, v0
	v_cmp_eq_u32_e32 vcc, 0, v0
	s_waitcnt vmcnt(0)
	s_and_saveexec_b64 s[12:13], vcc
	s_cbranch_execz .LBB0_1486
	s_bcnt1_i32_b64 s3, s[10:11]
	v_mov_b32_e32 v0, 0x2000
	v_mov_b32_e32 v1, s3
.LBB0_1486:
	s_or_b64 exec, exec, s[12:13]
	s_waitcnt vmcnt(0)
	s_branch .LBB0_1487
